# retention read-out loop: all six row loads and the four gain loads issued before the first wait (one round trip per row instead of two)
# baseline (speedup 1.0000x reference)
; __device__ __forceinline__ float bf2f(bf16_t v) { return __uint_as_float((unsigned)v << 16); }
; __device__ __forceinline__ u32x4 pack8(const float* v) { u32x4 w; w.x = cvt_pk_bf16(v[0], v[1]); w.y = cvt_pk_bf16(v[2], v[3]); w.z = cvt_pk_bf16(v[4], v[5]); w.w = cvt_pk_bf16(v[6], v[7]); return w; }
; __global__ void __launch_bounds__(512) mk_fwd(Params P) {
;     ...
;             for (int row = gw; row < M; row += NGW) { const size_t off = (size_t)row * 1024 + lane * 16;
;                 const bf16x8 a0 = __builtin_nontemporal_load((const bf16x8*)(OF + off)), a1 = __builtin_nontemporal_load((const bf16x8*)(OF + off + 8)), b0 = __builtin_nontemporal_load((const bf16x8*)(OB + off)), b1 = __builtin_nontemporal_load((const bf16x8*)(OB + off + 8));
;                 const bf16x8 g0 = *(const bf16x8*)(Gb + off), g1 = *(const bf16x8*)(Gb + off + 8);
;                 float o[16]; float s = 0.f;
; #pragma unroll
;                 for (int e = 0; e < 8; ++e) { o[e] = bf2f((bf16_t)a0[e]) + bf2f((bf16_t)b0[e]); o[8 + e] = bf2f((bf16_t)a1[e]) + bf2f((bf16_t)b1[e]); }
; #pragma unroll
;                 for (int e = 0; e < 16; ++e) s += o[e] * o[e];
;                 s += __shfl_xor(s, 1); s += __shfl_xor(s, 2); s += __shfl_xor(s, 4);
;                 const float rinv = rsqrtf(s * (1.f / 128.f) + EPS);
; #pragma unroll
;                 for (int e = 0; e < 8; ++e) { o[e] = o[e] * rinv * P.in[20][v0 + e] * bf2f((bf16_t)g0[e]); o[8 + e] = o[8 + e] * rinv * P.in[20][v0 + 8 + e] * bf2f((bf16_t)g1[e]); }
;                 *(u32x4*)(A2b + off) = pack8(o); *(u32x4*)(A2b + off + 8) = pack8(o + 8); }
.LBB0_46:
	v_add_co_u32_e32 v0, vcc, 0xfbbffff0, v6
	s_add_i32 s3, s3, s42
	s_nop 0
	v_addc_co_u32_e32 v1, vcc, -1, v7, vcc
	flat_load_dwordx4 v[12:15], v[0:1] nt
	v_add_co_u32_e32 v0, vcc, 0xfbc00000, v6
	s_cmpk_gt_i32 s3, 0x43ff
	s_nop 0
	v_addc_co_u32_e32 v1, vcc, -1, v7, vcc
	flat_load_dwordx4 v[16:19], v[0:1] nt
	v_add_co_u32_e32 v0, vcc, 0xfddffff0, v6
	s_nop 1
	v_addc_co_u32_e32 v1, vcc, -1, v7, vcc
	flat_load_dwordx4 v[20:23], v[0:1] nt
	v_add_co_u32_e32 v0, vcc, 0xfde00000, v6
	s_nop 1
	v_addc_co_u32_e32 v1, vcc, -1, v7, vcc
	flat_load_dwordx4 v[24:27], v[0:1] nt
	v_add_co_u32_e32 v0, vcc, 0xf11ffff0, v6
	s_nop 1
	v_addc_co_u32_e32 v1, vcc, -1, v7, vcc
	flat_load_dwordx4 v[28:31], v[0:1]
	v_add_co_u32_e32 v0, vcc, 0xf1200000, v6
	s_nop 1
	v_addc_co_u32_e32 v1, vcc, -1, v7, vcc
	flat_load_dwordx4 v[0:3], v[0:1]
	s_nop 0
	global_load_dwordx4 v[32:35], v[4:5], off offset:48
	global_load_dwordx4 v[36:39], v[4:5], off offset:32
	global_load_dwordx4 v[40:43], v[4:5], off offset:16
	global_load_dwordx4 v[44:47], v[4:5], off
	s_waitcnt vmcnt(0) lgkmcnt(0)
	v_and_b32_e32 v51, 0xffff0000, v13
	v_lshlrev_b32_e32 v50, 16, v13
	v_and_b32_e32 v13, 0xffff0000, v12
	v_lshlrev_b32_e32 v12, 16, v12
	v_and_b32_e32 v49, 0xffff0000, v15
	v_lshlrev_b32_e32 v48, 16, v15
	v_and_b32_e32 v15, 0xffff0000, v14
	v_lshlrev_b32_e32 v14, 16, v14
	v_lshlrev_b32_e32 v52, 16, v19
	v_and_b32_e32 v53, 0xffff0000, v19
	v_and_b32_e32 v19, 0xffff0000, v18
	v_lshlrev_b32_e32 v18, 16, v18
	v_and_b32_e32 v55, 0xffff0000, v17
	v_lshlrev_b32_e32 v54, 16, v17
	v_and_b32_e32 v17, 0xffff0000, v16
	v_lshlrev_b32_e32 v16, 16, v16
	v_and_b32_e32 v59, 0xffff0000, v21
	v_lshlrev_b32_e32 v58, 16, v21
	v_and_b32_e32 v21, 0xffff0000, v20
	v_lshlrev_b32_e32 v20, 16, v20
	v_and_b32_e32 v57, 0xffff0000, v23
	v_lshlrev_b32_e32 v56, 16, v23
	v_and_b32_e32 v23, 0xffff0000, v22
	v_lshlrev_b32_e32 v22, 16, v22
	v_lshlrev_b32_e32 v60, 16, v27
	v_and_b32_e32 v61, 0xffff0000, v27
	v_and_b32_e32 v27, 0xffff0000, v26
	v_lshlrev_b32_e32 v26, 16, v26
	v_and_b32_e32 v63, 0xffff0000, v25
	v_lshlrev_b32_e32 v62, 16, v25
	v_pk_add_f32 v[12:13], v[12:13], v[20:21]
	v_pk_add_f32 v[14:15], v[14:15], v[22:23]
	v_pk_add_f32 v[22:23], v[50:51], v[58:59]
	v_pk_add_f32 v[18:19], v[18:19], v[26:27]
	v_pk_add_f32 v[26:27], v[54:55], v[62:63]
	v_pk_mul_f32 v[54:55], v[12:13], v[12:13]
	v_pk_add_f32 v[20:21], v[52:53], v[60:61]
	v_pk_mul_f32 v[52:53], v[22:23], v[22:23]
	v_add_f32_e32 v11, v54, v55
	v_add_f32_e32 v11, v11, v52
	v_pk_mul_f32 v[50:51], v[14:15], v[14:15]
	v_add_f32_e32 v11, v11, v53
	v_and_b32_e32 v25, 0xffff0000, v24
	v_lshlrev_b32_e32 v24, 16, v24
	v_pk_add_f32 v[48:49], v[48:49], v[56:57]
	v_add_f32_e32 v11, v11, v50
	v_pk_add_f32 v[16:17], v[16:17], v[24:25]
	v_pk_mul_f32 v[24:25], v[48:49], v[48:49]
	v_add_f32_e32 v11, v11, v51
	v_add_f32_e32 v11, v11, v24
	v_pk_mul_f32 v[62:63], v[16:17], v[16:17]
	v_add_f32_e32 v11, v11, v25
	v_add_f32_e32 v11, v11, v62
	v_pk_mul_f32 v[60:61], v[26:27], v[26:27]
	v_add_f32_e32 v11, v11, v63
	v_add_f32_e32 v11, v11, v60
	v_pk_mul_f32 v[58:59], v[18:19], v[18:19]
	v_add_f32_e32 v11, v11, v61
	v_add_f32_e32 v11, v11, v58
	v_pk_mul_f32 v[56:57], v[20:21], v[20:21]
	v_add_f32_e32 v11, v11, v59
	v_add_f32_e32 v11, v11, v56
	v_add_f32_e32 v11, v11, v57
	ds_bpermute_b32 v50, v8, v11
	v_and_b32_e32 v53, 0xffff0000, v2
	v_lshlrev_b32_e32 v52, 16, v2
	v_and_b32_e32 v55, 0xffff0000, v1
	v_lshlrev_b32_e32 v54, 16, v1
	s_waitcnt lgkmcnt(0)
	v_add_f32_e32 v11, v11, v50
	ds_bpermute_b32 v50, v9, v11
	v_and_b32_e32 v1, 0xffff0000, v0
	v_lshlrev_b32_e32 v0, 16, v0
	v_and_b32_e32 v51, 0xffff0000, v29
	v_and_b32_e32 v25, 0xffff0000, v31
	s_waitcnt lgkmcnt(0)
	v_add_f32_e32 v2, v11, v50
	ds_bpermute_b32 v11, v10, v2
	v_lshlrev_b32_e32 v50, 16, v29
	v_lshlrev_b32_e32 v24, 16, v31
	v_and_b32_e32 v31, 0xffff0000, v30
	v_lshlrev_b32_e32 v30, 16, v30
	s_waitcnt lgkmcnt(0)
	v_add_f32_e32 v2, v2, v11
	v_fmamk_f32 v2, v2, 0x3c000000, v186
	v_mul_f32_e32 v11, 0x4b800000, v2
	v_cmp_gt_f32_e32 vcc, s53, v2
	v_and_b32_e32 v29, 0xffff0000, v28
	v_lshlrev_b32_e32 v28, 16, v28
	v_cndmask_b32_e32 v2, v2, v11, vcc
	v_rsq_f32_e32 v2, v2
	s_nop 0
	v_mul_f32_e32 v11, 0x45800000, v2
	v_cndmask_b32_e32 v2, v2, v11, vcc
	v_pk_mul_f32 v[16:17], v[2:3], v[16:17] op_sel_hi:[0,1]
	v_pk_mul_f32 v[16:17], v[36:37], v[16:17]
	v_pk_mul_f32 v[12:13], v[2:3], v[12:13] op_sel_hi:[0,1]
	v_pk_mul_f32 v[16:17], v[16:17], v[0:1]
	v_pk_mul_f32 v[0:1], v[2:3], v[22:23] op_sel_hi:[0,1]
	v_pk_mul_f32 v[0:1], v[0:1], v[46:47]
	v_pk_mul_f32 v[12:13], v[12:13], v[44:45]
	v_pk_mul_f32 v[22:23], v[0:1], v[50:51]
	v_pk_mul_f32 v[0:1], v[2:3], v[26:27] op_sel_hi:[0,1]
	v_pk_mul_f32 v[0:1], v[38:39], v[0:1]
	v_pk_mul_f32 v[12:13], v[12:13], v[28:29]
	v_pk_mul_f32 v[26:27], v[0:1], v[54:55]
	v_pk_mul_f32 v[0:1], v[2:3], v[14:15] op_sel_hi:[0,1]
	v_pk_mul_f32 v[0:1], v[0:1], v[40:41]
	s_nop 0
	v_pk_mul_f32 v[14:15], v[0:1], v[30:31]
	v_pk_mul_f32 v[0:1], v[2:3], v[18:19] op_sel_hi:[0,1]
	v_pk_mul_f32 v[0:1], v[32:33], v[0:1]
	s_nop 0
	v_pk_mul_f32 v[18:19], v[0:1], v[52:53]
	v_pk_mul_f32 v[0:1], v[2:3], v[48:49] op_sel_hi:[0,1]
	v_pk_mul_f32 v[0:1], v[0:1], v[42:43]
	s_nop 0
	v_pk_mul_f32 v[24:25], v[0:1], v[24:25]
	v_pk_mul_f32 v[0:1], v[2:3], v[20:21] op_sel_hi:[0,1]
	v_pk_mul_f32 v[0:1], v[34:35], v[0:1]
	v_and_b32_e32 v21, 0xffff0000, v3
	v_lshlrev_b32_e32 v20, 16, v3
	v_pk_mul_f32 v[20:21], v[0:1], v[20:21]
	v_cvt_pk_bf16_f32 v0, v12, v13
	v_add_co_u32_e32 v12, vcc, -16, v6
	v_cvt_pk_bf16_f32 v1, v22, v23
	v_cvt_pk_bf16_f32 v2, v14, v15
	v_cvt_pk_bf16_f32 v3, v24, v25
	v_addc_co_u32_e32 v13, vcc, -1, v7, vcc
	flat_store_dwordx4 v[12:13], v[0:3]
	s_nop 1
	v_cvt_pk_bf16_f32 v0, v16, v17
	v_cvt_pk_bf16_f32 v1, v26, v27
	v_cvt_pk_bf16_f32 v2, v18, v19
	v_cvt_pk_bf16_f32 v3, v20, v21
	flat_store_dwordx4 v[6:7], v[0:3]
	v_lshl_add_u64 v[6:7], v[6:7], 0, s[6:7]
	s_cbranch_scc0 .LBB0_46
